# no grid barrier between the split-K projection GEMMs and the combine: per-row-tile completion counters (8 units each), combine spins on its row tile's counter and reads the partials with sc1 loads
# speedup vs baseline: 1.0345x; 1.0235x over previous
.LBB0_209:
	s_load_dwordx2 s[4:5], s[66:67], 0x100
	v_mov_b32_e32 v0, 0x20178
	ds_read_b32 v18, v0
	v_readlane_b32 s6, v255, 0
	s_nop 3
	s_lshr_b32 s6, s6, 3
	s_lshl_b32 s6, s6, 5
	s_add_u32 s6, s6, 0xe803a00
	s_waitcnt lgkmcnt(0)
	s_add_u32 s4, s4, s6
	s_addc_u32 s5, s5, 0
.Lcmb_poll:
	global_load_dword v19, v1, s[4:5] sc1
	s_waitcnt vmcnt(0)
	v_cmp_le_u32_e32 vcc, v18, v19
	s_cbranch_vccnz .Lcmb_go
	s_sleep 2
	s_branch .Lcmb_poll

.LBB0_213:
	v_lshlrev_b32_e32 v0, 2, v132
	global_load_dwordx4 v[78:81], v0, s[42:43]
	s_lshl_b64 s[38:39], s[4:5], 11
	s_add_u32 s46, s1, s38
	s_addc_u32 s47, s0, s39
	s_add_u32 s48, s2, s38
	s_addc_u32 s49, s3, s39
	s_and_b64 vcc, exec, s[20:21]
	v_lshlrev_b32_e32 v20, 1, v132
	s_cbranch_vccz .LBB0_215
	global_load_dwordx2 v[162:163], v20, s[46:47] sc1
	global_load_dwordx2 v[196:197], v20, s[48:49] sc1
.LBB0_215:
	v_lshl_add_u64 v[18:19], s[42:43], 0, v[0:1]
	global_load_dwordx4 v[74:77], v[18:19], off offset:1024
	v_cndmask_b32_e64 v21, 0, 1, s[20:21]
	v_cmp_ne_u32_e64 s[6:7], 1, v21
	s_andn2_b64 vcc, exec, s[20:21]
	s_cbranch_vccnz .LBB0_231
	global_load_dwordx2 v[158:159], v20, s[46:47] offset:512 sc1
	global_load_dwordx2 v[192:193], v20, s[48:49] offset:512 sc1
	global_load_dwordx4 v[70:73], v[18:19], off offset:2048
	s_and_b64 vcc, exec, s[6:7]
	s_cbranch_vccz .LBB0_232

.LBB0_218:
	global_load_dwordx2 v[150:151], v20, s[46:47] offset:1536 sc1
	global_load_dwordx2 v[188:189], v20, s[48:49] offset:1536 sc1
.LBB0_219:
	s_add_u32 s46, s42, 0x1000
	s_addc_u32 s47, s43, 0
	global_load_dwordx4 v[58:61], v0, s[46:47]
	s_and_b64 vcc, exec, s[6:7]
	v_lshl_add_u64 v[82:83], s[36:37], 0, v[144:145]
	s_cbranch_vccnz .LBB0_221
	v_add_co_u32_e32 v18, vcc, 0x1000000, v82
	s_nop 1
	v_addc_co_u32_e32 v19, vcc, 0, v83, vcc
	global_load_dwordx2 v[178:179], v[82:83], off offset:2048 sc1
	global_load_dwordx2 v[216:217], v[18:19], off offset:2048 sc1
.LBB0_221:
	v_or_b32_e32 v18, 0x100, v132
	v_lshlrev_b32_e32 v38, 2, v18
	global_load_dwordx4 v[54:57], v38, s[46:47]
	s_and_b64 vcc, exec, s[6:7]
	s_cbranch_vccnz .LBB0_223
	v_add_co_u32_e32 v18, vcc, 0x1000000, v82
	s_nop 1
	v_addc_co_u32_e32 v19, vcc, 0, v83, vcc
	global_load_dwordx2 v[174:175], v[82:83], off offset:2560 sc1
	global_load_dwordx2 v[212:213], v[18:19], off offset:2560 sc1
.LBB0_223:
	v_or_b32_e32 v18, 0x200, v132
	v_lshlrev_b32_e32 v46, 2, v18
	global_load_dwordx4 v[62:65], v46, s[46:47]
	s_and_b64 vcc, exec, s[6:7]
	s_cbranch_vccnz .LBB0_225
	v_add_co_u32_e32 v18, vcc, 0x1000000, v82
	s_nop 1
	v_addc_co_u32_e32 v19, vcc, 0, v83, vcc
	global_load_dwordx2 v[170:171], v[82:83], off offset:3072 sc1
	global_load_dwordx2 v[208:209], v[18:19], off offset:3072 sc1
.LBB0_225:
	v_or_b32_e32 v18, 0x300, v132
	v_lshlrev_b32_e32 v50, 2, v18
	global_load_dwordx4 v[42:45], v50, s[46:47]
	s_and_b64 vcc, exec, s[6:7]
	s_cbranch_vccnz .LBB0_227
	v_add_co_u32_e32 v18, vcc, 0x1000000, v82
	s_nop 1
	v_addc_co_u32_e32 v19, vcc, 0, v83, vcc
	global_load_dwordx2 v[166:167], v[82:83], off offset:3584 sc1
	global_load_dwordx2 v[204:205], v[18:19], off offset:3584 sc1
.LBB0_227:
	s_add_u32 s46, s42, 0x2000
	s_addc_u32 s47, s43, 0
	global_load_dwordx4 v[18:21], v0, s[46:47]
	s_and_b64 vcc, exec, s[6:7]
	s_cbranch_vccnz .LBB0_233
	v_add_co_u32_e32 v22, vcc, 0x1000, v82
	s_nop 1
	v_addc_co_u32_e32 v23, vcc, 0, v83, vcc
	v_add_co_u32_e32 v24, vcc, 0x1001000, v82
	s_nop 1
	v_addc_co_u32_e32 v25, vcc, 0, v83, vcc
	global_load_dwordx2 v[180:181], v[22:23], off sc1
	global_load_dwordx2 v[218:219], v[24:25], off sc1
	s_nop 0
	global_load_dwordx4 v[22:25], v38, s[46:47]
	s_and_b64 vcc, exec, s[6:7]
	s_cbranch_vccz .LBB0_234

.LBB0_230:
	v_add_co_u32_e32 v30, vcc, 0x1000, v82
	s_nop 1
	v_addc_co_u32_e32 v31, vcc, 0, v83, vcc
	v_add_co_u32_e32 v32, vcc, 0x1001000, v82
	s_nop 1
	v_addc_co_u32_e32 v33, vcc, 0, v83, vcc
	global_load_dwordx2 v[172:173], v[30:31], off offset:1024 sc1
	global_load_dwordx2 v[210:211], v[32:33], off offset:1024 sc1
	s_nop 0
	global_load_dwordx4 v[30:33], v50, s[46:47]
	s_and_b64 vcc, exec, s[6:7]
	s_cbranch_vccz .LBB0_236
	s_branch .LBB0_237

.LBB0_232:
	global_load_dwordx2 v[154:155], v20, s[46:47] offset:1024 sc1
	global_load_dwordx2 v[190:191], v20, s[48:49] offset:1024 sc1
	global_load_dwordx4 v[66:69], v[18:19], off offset:3072
	s_and_b64 vcc, exec, s[6:7]
	s_cbranch_vccz .LBB0_218
	s_branch .LBB0_219

.LBB0_234:
	v_add_co_u32_e32 v26, vcc, 0x1000, v82
	s_nop 1
	v_addc_co_u32_e32 v27, vcc, 0, v83, vcc
	v_add_co_u32_e32 v28, vcc, 0x1001000, v82
	s_nop 1
	v_addc_co_u32_e32 v29, vcc, 0, v83, vcc
	global_load_dwordx2 v[176:177], v[26:27], off offset:512 sc1
	global_load_dwordx2 v[214:215], v[28:29], off offset:512 sc1
	s_nop 0
	global_load_dwordx4 v[26:29], v46, s[46:47]
	s_and_b64 vcc, exec, s[6:7]
	s_cbranch_vccz .LBB0_230

.LBB0_236:
	v_add_co_u32_e32 v34, vcc, 0x1000, v82
	s_nop 1
	v_addc_co_u32_e32 v35, vcc, 0, v83, vcc
	v_add_co_u32_e32 v36, vcc, 0x1001000, v82
	s_nop 1
	v_addc_co_u32_e32 v37, vcc, 0, v83, vcc
	global_load_dwordx2 v[168:169], v[34:35], off offset:1536 sc1
	global_load_dwordx2 v[206:207], v[36:37], off offset:1536 sc1
.LBB0_237:
	s_add_u32 s42, s42, 0x3000
	s_addc_u32 s43, s43, 0
	global_load_dwordx4 v[34:37], v0, s[42:43]
	s_and_b64 vcc, exec, s[6:7]
	s_cbranch_vccnz .LBB0_241
	v_add_co_u32_e32 v40, vcc, 0x1000, v82
	s_nop 1
	v_addc_co_u32_e32 v41, vcc, 0, v83, vcc
	v_add_co_u32_e32 v48, vcc, 0x1001000, v82
	s_nop 1
	v_addc_co_u32_e32 v49, vcc, 0, v83, vcc
	global_load_dwordx2 v[164:165], v[40:41], off offset:2048 sc1
	global_load_dwordx2 v[202:203], v[48:49], off offset:2048 sc1
	s_nop 0
	global_load_dwordx4 v[38:41], v38, s[42:43]
	s_and_b64 vcc, exec, s[6:7]
	s_cbranch_vccz .LBB0_242

.LBB0_240:
	v_add_co_u32_e32 v52, vcc, 0x1000, v82
	s_nop 1
	v_addc_co_u32_e32 v53, vcc, 0, v83, vcc
	v_add_co_u32_e32 v84, vcc, 0x1001000, v82
	s_nop 1
	v_addc_co_u32_e32 v85, vcc, 0, v83, vcc
	global_load_dwordx2 v[156:157], v[52:53], off offset:3072 sc1
	global_load_dwordx2 v[198:199], v[84:85], off offset:3072 sc1
	s_nop 0
	global_load_dwordx4 v[50:53], v50, s[42:43]
	s_and_b64 vcc, exec, s[6:7]
	s_cbranch_vccz .LBB0_244
	s_branch .LBB0_245

.LBB0_242:
	v_add_co_u32_e32 v48, vcc, 0x1000, v82
	s_nop 1
	v_addc_co_u32_e32 v49, vcc, 0, v83, vcc
	v_add_co_u32_e32 v52, vcc, 0x1001000, v82
	s_nop 1
	v_addc_co_u32_e32 v53, vcc, 0, v83, vcc
	global_load_dwordx2 v[160:161], v[48:49], off offset:2560 sc1
	global_load_dwordx2 v[200:201], v[52:53], off offset:2560 sc1
	s_nop 0
	global_load_dwordx4 v[46:49], v46, s[42:43]
	s_and_b64 vcc, exec, s[6:7]
	s_cbranch_vccz .LBB0_240

.LBB0_244:
	v_add_co_u32_e32 v84, vcc, 0x1000, v82
	s_nop 1
	v_addc_co_u32_e32 v85, vcc, 0, v83, vcc
	v_add_co_u32_e32 v82, vcc, 0x1001000, v82
	s_nop 1
	v_addc_co_u32_e32 v83, vcc, 0, v83, vcc
	global_load_dwordx2 v[152:153], v[84:85], off offset:3584 sc1
	global_load_dwordx2 v[194:195], v[82:83], off offset:3584 sc1

.LBB0_540:
	s_waitcnt vmcnt(0)
	s_waitcnt vmcnt(0) lgkmcnt(0)
	s_barrier
	s_and_saveexec_b64 s[4:5], s[8:9]
	v_readlane_b32 s0, v255, 0
	s_nop 3
	s_and_b32 s1, s0, 7
	s_lshl_b32 s1, s1, 5
	s_lshr_b32 s0, s0, 3
	s_add_i32 s0, s0, s1
	s_lshr_b32 s1, s0, 6
	s_lshl_b32 s1, s1, 3
	s_and_b32 s0, s0, 7
	s_add_i32 s0, s0, s1
	s_lshl_b32 s0, s0, 5
	s_add_u32 s0, s0, 0xe803a00
	s_add_u32 s2, s6, s0
	s_addc_u32 s3, s7, 0
	v_mov_b32_e32 v0, 1
	v_mov_b32_e32 v2, 0
	global_atomic_add v2, v0, s[2:3]
	v_mov_b32_e32 v0, 0x20178
	v_mov_b32_e32 v2, 8
	ds_add_u32 v0, v2

.LBB0_1336:
	s_waitcnt vmcnt(0)
	s_waitcnt vmcnt(0) lgkmcnt(0)
	s_barrier
	s_and_saveexec_b64 s[4:5], s[8:9]
	v_readlane_b32 s0, v255, 0
	s_nop 3
	s_and_b32 s1, s0, 7
	s_lshl_b32 s1, s1, 5
	s_lshr_b32 s0, s0, 3
	s_add_i32 s0, s0, s1
	s_lshr_b32 s1, s0, 6
	s_lshl_b32 s1, s1, 3
	s_and_b32 s0, s0, 7
	s_add_i32 s0, s0, s1
	s_lshl_b32 s0, s0, 5
	s_add_u32 s0, s0, 0xe803a00
	s_add_u32 s2, s6, s0
	s_addc_u32 s3, s7, 0
	v_mov_b32_e32 v0, 1
	v_mov_b32_e32 v2, 0
	global_atomic_add v2, v0, s[2:3]
	v_mov_b32_e32 v0, 0x20178
	v_mov_b32_e32 v2, 8
	ds_add_u32 v0, v2
	s_getpc_b64 s[98:99]
